# skinny16 K-loops (P2 tail x2, P5) fully unrolled with 20 k-steps of loads in flight and exact counted vmcnt
# baseline (speedup 1.0000x reference)
; __device__ __forceinline__ f32x4 skinny16(const bf16_t* A, int lda, const bf16_t* Bt, int ldb, int K, int lane) {
;     const int r = lane & 15, q = lane >> 4;
;     const bf16x8* ap = (const bf16x8*)(A + (size_t)r * lda + q * 8);
;     const bf16x8* bp = (const bf16x8*)(Bt + (size_t)r * ldb + q * 8);
;     f32x4 acc0 = {0.f, 0.f, 0.f, 0.f}, acc1 = {0.f, 0.f, 0.f, 0.f};
; #pragma unroll 1
;     for (int k = 0; k < K / 32; k += 16) {
;         bf16x8 a[16], b[16];
; #pragma unroll
;         for (int i = 0; i < 16; ++i) { a[i] = ap[(k + i) * 4]; b[i] = bp[(k + i) * 4]; }
; #pragma unroll
;         for (int i = 0; i < 16; i += 2) { acc0 = __builtin_amdgcn_mfma_f32_16x16x32_bf16(a[i], b[i], acc0, 0, 0, 0); acc1 = __builtin_amdgcn_mfma_f32_16x16x32_bf16(a[i + 1], b[i + 1], acc1, 0, 0, 0); }
;     }
;     return acc0 + acc1;
; }
; __global__ void __launch_bounds__(512, 2) mega(Args a) {
;     ...
;                 } else { const int pt = task - 8;
;                     const f32x4 acc = skinny16(hb + (size_t)pt * 16 * DM, DM, Wi + (size_t)NZ * DM, DM, DM, lane);
; #pragma unroll
;                     for (int j = 0; j < 4; ++j) ba[(size_t)(pt * 16 + q8 * 4 + j) * 16 + r] = acc[j];
.LBB0_363:
	global_load_dwordx4 v[68:71], v[16:17], off offset:-512
	global_load_dwordx4 v[72:75], v[18:19], off offset:-512
	global_load_dwordx4 v[76:79], v[16:17], off offset:-448
	global_load_dwordx4 v[80:83], v[18:19], off offset:-448
	global_load_dwordx4 v[84:87], v[16:17], off offset:-384
	global_load_dwordx4 v[88:91], v[18:19], off offset:-384
	global_load_dwordx4 v[92:95], v[16:17], off offset:-320
	global_load_dwordx4 v[96:99], v[18:19], off offset:-320
	global_load_dwordx4 v[100:103], v[16:17], off offset:-256
	global_load_dwordx4 v[104:107], v[18:19], off offset:-256
	global_load_dwordx4 v[108:111], v[16:17], off offset:-192
	global_load_dwordx4 v[112:115], v[18:19], off offset:-192
	global_load_dwordx4 v[116:119], v[16:17], off offset:-128
	global_load_dwordx4 v[120:123], v[18:19], off offset:-128
	global_load_dwordx4 v[124:127], v[16:17], off offset:-64
	global_load_dwordx4 v[128:131], v[18:19], off offset:-64
	global_load_dwordx4 v[132:135], v[16:17], off offset:0
	global_load_dwordx4 v[136:139], v[18:19], off offset:0
	global_load_dwordx4 v[140:143], v[16:17], off offset:64
	global_load_dwordx4 v[144:147], v[18:19], off offset:64
	global_load_dwordx4 v[148:151], v[16:17], off offset:128
	global_load_dwordx4 v[164:167], v[18:19], off offset:128
	global_load_dwordx4 v[168:171], v[16:17], off offset:192
	global_load_dwordx4 v[172:175], v[18:19], off offset:192
	global_load_dwordx4 v[176:179], v[16:17], off offset:256
	global_load_dwordx4 v[180:183], v[18:19], off offset:256
	global_load_dwordx4 v[184:187], v[16:17], off offset:320
	global_load_dwordx4 v[188:191], v[18:19], off offset:320
	global_load_dwordx4 v[204:207], v[16:17], off offset:384
	global_load_dwordx4 v[208:211], v[18:19], off offset:384
	global_load_dwordx4 v[212:215], v[16:17], off offset:448
	global_load_dwordx4 v[216:219], v[18:19], off offset:448
	global_load_dwordx4 v[220:223], v[16:17], off offset:512
	global_load_dwordx4 v[224:227], v[18:19], off offset:512
	global_load_dwordx4 v[228:231], v[16:17], off offset:576
	global_load_dwordx4 v[232:235], v[18:19], off offset:576
	global_load_dwordx4 v[236:239], v[16:17], off offset:640
	global_load_dwordx4 v[240:243], v[18:19], off offset:640
	global_load_dwordx4 v[244:247], v[16:17], off offset:704
	global_load_dwordx4 v[248:251], v[18:19], off offset:704
	s_waitcnt vmcnt(38)
	v_mfma_f32_16x16x32_bf16 v[4:7], v[68:71], v[72:75], v[4:7]
	global_load_dwordx4 v[68:71], v[16:17], off offset:768
	global_load_dwordx4 v[72:75], v[18:19], off offset:768
	s_waitcnt vmcnt(38)
	v_mfma_f32_16x16x32_bf16 v[0:3], v[76:79], v[80:83], v[0:3]
	global_load_dwordx4 v[76:79], v[16:17], off offset:832
	global_load_dwordx4 v[80:83], v[18:19], off offset:832
	s_waitcnt vmcnt(38)
	v_mfma_f32_16x16x32_bf16 v[4:7], v[84:87], v[88:91], v[4:7]
	global_load_dwordx4 v[84:87], v[16:17], off offset:896
	global_load_dwordx4 v[88:91], v[18:19], off offset:896
	s_waitcnt vmcnt(38)
	v_mfma_f32_16x16x32_bf16 v[0:3], v[92:95], v[96:99], v[0:3]
	global_load_dwordx4 v[92:95], v[16:17], off offset:960
	global_load_dwordx4 v[96:99], v[18:19], off offset:960
	s_waitcnt vmcnt(38)
	v_mfma_f32_16x16x32_bf16 v[4:7], v[100:103], v[104:107], v[4:7]
	global_load_dwordx4 v[100:103], v[16:17], off offset:1024
	global_load_dwordx4 v[104:107], v[18:19], off offset:1024
	s_waitcnt vmcnt(38)
	v_mfma_f32_16x16x32_bf16 v[0:3], v[108:111], v[112:115], v[0:3]
	global_load_dwordx4 v[108:111], v[16:17], off offset:1088
	global_load_dwordx4 v[112:115], v[18:19], off offset:1088
	s_waitcnt vmcnt(38)
	v_mfma_f32_16x16x32_bf16 v[4:7], v[116:119], v[120:123], v[4:7]
	global_load_dwordx4 v[116:119], v[16:17], off offset:1152
	global_load_dwordx4 v[120:123], v[18:19], off offset:1152
	s_waitcnt vmcnt(38)
	v_mfma_f32_16x16x32_bf16 v[0:3], v[124:127], v[128:131], v[0:3]
	global_load_dwordx4 v[124:127], v[16:17], off offset:1216
	global_load_dwordx4 v[128:131], v[18:19], off offset:1216
	s_waitcnt vmcnt(38)
	v_mfma_f32_16x16x32_bf16 v[4:7], v[132:135], v[136:139], v[4:7]
	global_load_dwordx4 v[132:135], v[16:17], off offset:1280
	global_load_dwordx4 v[136:139], v[18:19], off offset:1280
	s_waitcnt vmcnt(38)
	v_mfma_f32_16x16x32_bf16 v[0:3], v[140:143], v[144:147], v[0:3]
	global_load_dwordx4 v[140:143], v[16:17], off offset:1344
	global_load_dwordx4 v[144:147], v[18:19], off offset:1344
	s_waitcnt vmcnt(38)
	v_mfma_f32_16x16x32_bf16 v[4:7], v[148:151], v[164:167], v[4:7]
	global_load_dwordx4 v[148:151], v[16:17], off offset:1408
	global_load_dwordx4 v[164:167], v[18:19], off offset:1408
	s_waitcnt vmcnt(38)
	v_mfma_f32_16x16x32_bf16 v[0:3], v[168:171], v[172:175], v[0:3]
	global_load_dwordx4 v[168:171], v[16:17], off offset:1472
	global_load_dwordx4 v[172:175], v[18:19], off offset:1472
	s_waitcnt vmcnt(38)
	v_mfma_f32_16x16x32_bf16 v[4:7], v[176:179], v[180:183], v[4:7]
	global_load_dwordx4 v[176:179], v[16:17], off offset:1536
	global_load_dwordx4 v[180:183], v[18:19], off offset:1536
	s_waitcnt vmcnt(38)
	v_mfma_f32_16x16x32_bf16 v[0:3], v[184:187], v[188:191], v[0:3]
	global_load_dwordx4 v[184:187], v[16:17], off offset:1600
	global_load_dwordx4 v[188:191], v[18:19], off offset:1600
	s_waitcnt vmcnt(38)
	v_mfma_f32_16x16x32_bf16 v[4:7], v[204:207], v[208:211], v[4:7]
	global_load_dwordx4 v[204:207], v[16:17], off offset:1664
	global_load_dwordx4 v[208:211], v[18:19], off offset:1664
	s_waitcnt vmcnt(38)
	v_mfma_f32_16x16x32_bf16 v[0:3], v[212:215], v[216:219], v[0:3]
	global_load_dwordx4 v[212:215], v[16:17], off offset:1728
	global_load_dwordx4 v[216:219], v[18:19], off offset:1728
	s_waitcnt vmcnt(38)
; __device__ __forceinline__ f32x4 skinny16(const bf16_t* A, int lda, const bf16_t* Bt, int ldb, int K, int lane) {
;     const int r = lane & 15, q = lane >> 4;
;     const bf16x8* ap = (const bf16x8*)(A + (size_t)r * lda + q * 8);
;     const bf16x8* bp = (const bf16x8*)(Bt + (size_t)r * ldb + q * 8);
;     f32x4 acc0 = {0.f, 0.f, 0.f, 0.f}, acc1 = {0.f, 0.f, 0.f, 0.f};
; #pragma unroll 1
;     for (int k = 0; k < K / 32; k += 16) {
;         bf16x8 a[16], b[16];
; #pragma unroll
;         for (int i = 0; i < 16; ++i) { a[i] = ap[(k + i) * 4]; b[i] = bp[(k + i) * 4]; }
; #pragma unroll
;         for (int i = 0; i < 16; i += 2) { acc0 = __builtin_amdgcn_mfma_f32_16x16x32_bf16(a[i], b[i], acc0, 0, 0, 0); acc1 = __builtin_amdgcn_mfma_f32_16x16x32_bf16(a[i + 1], b[i + 1], acc1, 0, 0, 0); }
;     }
;     return acc0 + acc1;
; }
	v_mfma_f32_16x16x32_bf16 v[4:7], v[220:223], v[224:227], v[4:7]
	global_load_dwordx4 v[220:223], v[16:17], off offset:1792
	global_load_dwordx4 v[224:227], v[18:19], off offset:1792
	s_waitcnt vmcnt(38)
	v_mfma_f32_16x16x32_bf16 v[0:3], v[228:231], v[232:235], v[0:3]
	global_load_dwordx4 v[228:231], v[16:17], off offset:1856
	global_load_dwordx4 v[232:235], v[18:19], off offset:1856
	s_waitcnt vmcnt(38)
	v_mfma_f32_16x16x32_bf16 v[4:7], v[236:239], v[240:243], v[4:7]
	global_load_dwordx4 v[236:239], v[16:17], off offset:1920
	global_load_dwordx4 v[240:243], v[18:19], off offset:1920
	s_waitcnt vmcnt(38)
	v_mfma_f32_16x16x32_bf16 v[0:3], v[244:247], v[248:251], v[0:3]
	global_load_dwordx4 v[244:247], v[16:17], off offset:1984
	global_load_dwordx4 v[248:251], v[18:19], off offset:1984
	s_waitcnt vmcnt(38)
	v_mfma_f32_16x16x32_bf16 v[4:7], v[68:71], v[72:75], v[4:7]
	global_load_dwordx4 v[68:71], v[16:17], off offset:2048
	global_load_dwordx4 v[72:75], v[18:19], off offset:2048
	s_waitcnt vmcnt(38)
	v_mfma_f32_16x16x32_bf16 v[0:3], v[76:79], v[80:83], v[0:3]
	global_load_dwordx4 v[76:79], v[16:17], off offset:2112
	global_load_dwordx4 v[80:83], v[18:19], off offset:2112
	s_waitcnt vmcnt(38)
	v_mfma_f32_16x16x32_bf16 v[4:7], v[84:87], v[88:91], v[4:7]
	global_load_dwordx4 v[84:87], v[16:17], off offset:2176
	global_load_dwordx4 v[88:91], v[18:19], off offset:2176
	s_waitcnt vmcnt(38)
	v_mfma_f32_16x16x32_bf16 v[0:3], v[92:95], v[96:99], v[0:3]
	global_load_dwordx4 v[92:95], v[16:17], off offset:2240
	global_load_dwordx4 v[96:99], v[18:19], off offset:2240
	s_waitcnt vmcnt(38)
	v_mfma_f32_16x16x32_bf16 v[4:7], v[100:103], v[104:107], v[4:7]
	global_load_dwordx4 v[100:103], v[16:17], off offset:2304
	global_load_dwordx4 v[104:107], v[18:19], off offset:2304
	s_waitcnt vmcnt(38)
	v_mfma_f32_16x16x32_bf16 v[0:3], v[108:111], v[112:115], v[0:3]
	global_load_dwordx4 v[108:111], v[16:17], off offset:2368
	global_load_dwordx4 v[112:115], v[18:19], off offset:2368
	s_waitcnt vmcnt(38)
	v_mfma_f32_16x16x32_bf16 v[4:7], v[116:119], v[120:123], v[4:7]
	global_load_dwordx4 v[116:119], v[16:17], off offset:2432
	global_load_dwordx4 v[120:123], v[18:19], off offset:2432
	s_waitcnt vmcnt(38)
	v_mfma_f32_16x16x32_bf16 v[0:3], v[124:127], v[128:131], v[0:3]
	global_load_dwordx4 v[124:127], v[16:17], off offset:2496
	global_load_dwordx4 v[128:131], v[18:19], off offset:2496
	s_waitcnt vmcnt(38)
	v_mfma_f32_16x16x32_bf16 v[4:7], v[132:135], v[136:139], v[4:7]
	global_load_dwordx4 v[132:135], v[16:17], off offset:2560
	global_load_dwordx4 v[136:139], v[18:19], off offset:2560
	s_waitcnt vmcnt(38)
	v_mfma_f32_16x16x32_bf16 v[0:3], v[140:143], v[144:147], v[0:3]
	global_load_dwordx4 v[140:143], v[16:17], off offset:2624
	global_load_dwordx4 v[144:147], v[18:19], off offset:2624
	s_waitcnt vmcnt(38)
	v_mfma_f32_16x16x32_bf16 v[4:7], v[148:151], v[164:167], v[4:7]
	global_load_dwordx4 v[148:151], v[16:17], off offset:2688
	global_load_dwordx4 v[164:167], v[18:19], off offset:2688
	s_waitcnt vmcnt(38)
	v_mfma_f32_16x16x32_bf16 v[0:3], v[168:171], v[172:175], v[0:3]
	global_load_dwordx4 v[168:171], v[16:17], off offset:2752
	global_load_dwordx4 v[172:175], v[18:19], off offset:2752
	s_waitcnt vmcnt(38)
	v_mfma_f32_16x16x32_bf16 v[4:7], v[176:179], v[180:183], v[4:7]
	global_load_dwordx4 v[176:179], v[16:17], off offset:2816
	global_load_dwordx4 v[180:183], v[18:19], off offset:2816
	s_waitcnt vmcnt(38)
	v_mfma_f32_16x16x32_bf16 v[0:3], v[184:187], v[188:191], v[0:3]
	global_load_dwordx4 v[184:187], v[16:17], off offset:2880
	global_load_dwordx4 v[188:191], v[18:19], off offset:2880
	s_waitcnt vmcnt(38)
	v_mfma_f32_16x16x32_bf16 v[4:7], v[204:207], v[208:211], v[4:7]
	global_load_dwordx4 v[204:207], v[16:17], off offset:2944
	global_load_dwordx4 v[208:211], v[18:19], off offset:2944
	s_waitcnt vmcnt(38)
	v_mfma_f32_16x16x32_bf16 v[0:3], v[212:215], v[216:219], v[0:3]
	global_load_dwordx4 v[212:215], v[16:17], off offset:3008
	global_load_dwordx4 v[216:219], v[18:19], off offset:3008
	s_waitcnt vmcnt(38)
; __device__ __forceinline__ f32x4 skinny16(const bf16_t* A, int lda, const bf16_t* Bt, int ldb, int K, int lane) {
;     const int r = lane & 15, q = lane >> 4;
;     const bf16x8* ap = (const bf16x8*)(A + (size_t)r * lda + q * 8);
;     const bf16x8* bp = (const bf16x8*)(Bt + (size_t)r * ldb + q * 8);
;     f32x4 acc0 = {0.f, 0.f, 0.f, 0.f}, acc1 = {0.f, 0.f, 0.f, 0.f};
; #pragma unroll 1
;     for (int k = 0; k < K / 32; k += 16) {
;         bf16x8 a[16], b[16];
; #pragma unroll
;         for (int i = 0; i < 16; ++i) { a[i] = ap[(k + i) * 4]; b[i] = bp[(k + i) * 4]; }
; #pragma unroll
;         for (int i = 0; i < 16; i += 2) { acc0 = __builtin_amdgcn_mfma_f32_16x16x32_bf16(a[i], b[i], acc0, 0, 0, 0); acc1 = __builtin_amdgcn_mfma_f32_16x16x32_bf16(a[i + 1], b[i + 1], acc1, 0, 0, 0); }
;     }
;     return acc0 + acc1;
; }
; __global__ void __launch_bounds__(512, 2) mega(Args a) {
;     ...
;                 } else { const int pt = task - 8;
;                     const f32x4 acc = skinny16(hb + (size_t)pt * 16 * DM, DM, Wi + (size_t)NZ * DM, DM, DM, lane);
; #pragma unroll
;                     for (int j = 0; j < 4; ++j) ba[(size_t)(pt * 16 + q8 * 4 + j) * 16 + r] = acc[j];
	v_mfma_f32_16x16x32_bf16 v[4:7], v[220:223], v[224:227], v[4:7]
	global_load_dwordx4 v[220:223], v[16:17], off offset:3072
	global_load_dwordx4 v[224:227], v[18:19], off offset:3072
	s_waitcnt vmcnt(38)
	v_mfma_f32_16x16x32_bf16 v[0:3], v[228:231], v[232:235], v[0:3]
	global_load_dwordx4 v[228:231], v[16:17], off offset:3136
	global_load_dwordx4 v[232:235], v[18:19], off offset:3136
	s_waitcnt vmcnt(38)
	v_mfma_f32_16x16x32_bf16 v[4:7], v[236:239], v[240:243], v[4:7]
	global_load_dwordx4 v[236:239], v[16:17], off offset:3200
	global_load_dwordx4 v[240:243], v[18:19], off offset:3200
	s_waitcnt vmcnt(38)
	v_mfma_f32_16x16x32_bf16 v[0:3], v[244:247], v[248:251], v[0:3]
	global_load_dwordx4 v[244:247], v[16:17], off offset:3264
	global_load_dwordx4 v[248:251], v[18:19], off offset:3264
	s_waitcnt vmcnt(38)
	v_mfma_f32_16x16x32_bf16 v[4:7], v[68:71], v[72:75], v[4:7]
	global_load_dwordx4 v[68:71], v[16:17], off offset:3328
	global_load_dwordx4 v[72:75], v[18:19], off offset:3328
	s_waitcnt vmcnt(38)
	v_mfma_f32_16x16x32_bf16 v[0:3], v[76:79], v[80:83], v[0:3]
	global_load_dwordx4 v[76:79], v[16:17], off offset:3392
	global_load_dwordx4 v[80:83], v[18:19], off offset:3392
	s_waitcnt vmcnt(38)
	v_mfma_f32_16x16x32_bf16 v[4:7], v[84:87], v[88:91], v[4:7]
	global_load_dwordx4 v[84:87], v[16:17], off offset:3456
	global_load_dwordx4 v[88:91], v[18:19], off offset:3456
	s_waitcnt vmcnt(38)
	v_mfma_f32_16x16x32_bf16 v[0:3], v[92:95], v[96:99], v[0:3]
	global_load_dwordx4 v[92:95], v[16:17], off offset:3520
	global_load_dwordx4 v[96:99], v[18:19], off offset:3520
	s_waitcnt vmcnt(38)
	v_mfma_f32_16x16x32_bf16 v[4:7], v[100:103], v[104:107], v[4:7]
	s_waitcnt vmcnt(36)
	v_mfma_f32_16x16x32_bf16 v[0:3], v[108:111], v[112:115], v[0:3]
	s_waitcnt vmcnt(34)
	v_mfma_f32_16x16x32_bf16 v[4:7], v[116:119], v[120:123], v[4:7]
	s_waitcnt vmcnt(32)
	v_mfma_f32_16x16x32_bf16 v[0:3], v[124:127], v[128:131], v[0:3]
	s_waitcnt vmcnt(30)
	v_mfma_f32_16x16x32_bf16 v[4:7], v[132:135], v[136:139], v[4:7]
	s_waitcnt vmcnt(28)
	v_mfma_f32_16x16x32_bf16 v[0:3], v[140:143], v[144:147], v[0:3]
	s_waitcnt vmcnt(26)
	v_mfma_f32_16x16x32_bf16 v[4:7], v[148:151], v[164:167], v[4:7]
	s_waitcnt vmcnt(24)
	v_mfma_f32_16x16x32_bf16 v[0:3], v[168:171], v[172:175], v[0:3]
	s_waitcnt vmcnt(22)
	v_mfma_f32_16x16x32_bf16 v[4:7], v[176:179], v[180:183], v[4:7]
	s_waitcnt vmcnt(20)
	v_mfma_f32_16x16x32_bf16 v[0:3], v[184:187], v[188:191], v[0:3]
	s_waitcnt vmcnt(18)
	v_mfma_f32_16x16x32_bf16 v[4:7], v[204:207], v[208:211], v[4:7]
	s_waitcnt vmcnt(16)
	v_mfma_f32_16x16x32_bf16 v[0:3], v[212:215], v[216:219], v[0:3]
	s_waitcnt vmcnt(14)
	v_mfma_f32_16x16x32_bf16 v[4:7], v[220:223], v[224:227], v[4:7]
	s_waitcnt vmcnt(12)
	v_mfma_f32_16x16x32_bf16 v[0:3], v[228:231], v[232:235], v[0:3]
	s_waitcnt vmcnt(10)
	v_mfma_f32_16x16x32_bf16 v[4:7], v[236:239], v[240:243], v[4:7]
	s_waitcnt vmcnt(8)
	v_mfma_f32_16x16x32_bf16 v[0:3], v[244:247], v[248:251], v[0:3]
	s_waitcnt vmcnt(6)
	v_mfma_f32_16x16x32_bf16 v[4:7], v[68:71], v[72:75], v[4:7]
	s_waitcnt vmcnt(4)
	v_mfma_f32_16x16x32_bf16 v[0:3], v[76:79], v[80:83], v[0:3]
	s_waitcnt vmcnt(2)
	v_mfma_f32_16x16x32_bf16 v[4:7], v[84:87], v[88:91], v[4:7]
	s_waitcnt vmcnt(0)
	v_mfma_f32_16x16x32_bf16 v[0:3], v[92:95], v[96:99], v[0:3]
	s_nop 1
	s_lshl_b32 s5, s8, 4
	s_addk_i32 s5, 0xff80
	s_nop 4
	v_pk_add_f32 v[0:1], v[4:5], v[0:1]
	v_or_b32_e32 v4, s5, v20
	v_mov_b32_e32 v5, v153
	v_pk_add_f32 v[2:3], v[6:7], v[2:3]
	v_lshlrev_b64 v[6:7], 6, v[4:5]
	v_lshl_add_u64 v[6:7], v[8:9], 0, v[6:7]
	global_store_dword v[6:7], v0, off
	v_or_b32_e32 v6, 1, v4
	v_mov_b32_e32 v7, v153
	v_lshlrev_b64 v[6:7], 6, v[6:7]
	v_lshl_add_u64 v[6:7], v[8:9], 0, v[6:7]
	global_store_dword v[6:7], v1, off
	v_or_b32_e32 v0, 2, v4
	v_mov_b32_e32 v1, v153
	v_lshlrev_b64 v[0:1], 6, v[0:1]
	v_lshl_add_u64 v[0:1], v[8:9], 0, v[0:1]
	global_store_dword v[0:1], v2, off
	v_or_b32_e32 v0, 3, v4
	v_mov_b32_e32 v1, v153
	v_lshlrev_b64 v[0:1], 6, v[0:1]
	v_lshl_add_u64 v[0:1], v[8:9], 0, v[0:1]
	s_mov_b64 s[6:7], 0
	global_store_dword v[0:1], v3, off

; __device__ __forceinline__ f32x4 skinny16(const bf16_t* A, int lda, const bf16_t* Bt, int ldb, int K, int lane) {
;     const int r = lane & 15, q = lane >> 4;
;     const bf16x8* ap = (const bf16x8*)(A + (size_t)r * lda + q * 8);
;     const bf16x8* bp = (const bf16x8*)(Bt + (size_t)r * ldb + q * 8);
;     f32x4 acc0 = {0.f, 0.f, 0.f, 0.f}, acc1 = {0.f, 0.f, 0.f, 0.f};
; #pragma unroll 1
;     for (int k = 0; k < K / 32; k += 16) {
;         bf16x8 a[16], b[16];
; #pragma unroll
;         for (int i = 0; i < 16; ++i) { a[i] = ap[(k + i) * 4]; b[i] = bp[(k + i) * 4]; }
; #pragma unroll
;         for (int i = 0; i < 16; i += 2) { acc0 = __builtin_amdgcn_mfma_f32_16x16x32_bf16(a[i], b[i], acc0, 0, 0, 0); acc1 = __builtin_amdgcn_mfma_f32_16x16x32_bf16(a[i + 1], b[i + 1], acc1, 0, 0, 0); }
;     }
;     return acc0 + acc1;
; }
; __global__ void __launch_bounds__(512, 2) mega(Args a) {
;     ...
;                 if (task < 8) { const int mt = task;
;                     const f32x4 acc = skinny16(hb + (size_t)(MP + mt * 16) * DM, DM, Wi + (size_t)NZ * DM, DM, DM, lane);
; #pragma unroll
;                     for (int j = 0; j < 4; ++j) zs[(size_t)(mt * 16 + q8 * 4 + j) * DINP + NZ + r] = acc[j];
.LBB0_367:
	v_lshl_add_u64 v[18:19], v[16:17], 0, s[6:7]
	v_lshl_add_u64 v[62:63], v[16:17], 0, s[40:41]
	global_load_dwordx4 v[68:71], v[18:19], off offset:-512
	global_load_dwordx4 v[72:75], v[62:63], off offset:-512
	global_load_dwordx4 v[76:79], v[18:19], off offset:-448
	global_load_dwordx4 v[80:83], v[62:63], off offset:-448
	global_load_dwordx4 v[84:87], v[18:19], off offset:-384
	global_load_dwordx4 v[88:91], v[62:63], off offset:-384
	global_load_dwordx4 v[92:95], v[18:19], off offset:-320
	global_load_dwordx4 v[96:99], v[62:63], off offset:-320
	global_load_dwordx4 v[100:103], v[18:19], off offset:-256
	global_load_dwordx4 v[104:107], v[62:63], off offset:-256
	global_load_dwordx4 v[108:111], v[18:19], off offset:-192
	global_load_dwordx4 v[112:115], v[62:63], off offset:-192
	global_load_dwordx4 v[116:119], v[18:19], off offset:-128
	global_load_dwordx4 v[120:123], v[62:63], off offset:-128
	global_load_dwordx4 v[124:127], v[18:19], off offset:-64
	global_load_dwordx4 v[128:131], v[62:63], off offset:-64
	global_load_dwordx4 v[132:135], v[18:19], off offset:0
	global_load_dwordx4 v[136:139], v[62:63], off offset:0
	global_load_dwordx4 v[140:143], v[18:19], off offset:64
	global_load_dwordx4 v[144:147], v[62:63], off offset:64
	global_load_dwordx4 v[148:151], v[18:19], off offset:128
	global_load_dwordx4 v[164:167], v[62:63], off offset:128
	global_load_dwordx4 v[168:171], v[18:19], off offset:192
	global_load_dwordx4 v[172:175], v[62:63], off offset:192
	global_load_dwordx4 v[176:179], v[18:19], off offset:256
	global_load_dwordx4 v[180:183], v[62:63], off offset:256
	global_load_dwordx4 v[184:187], v[18:19], off offset:320
	global_load_dwordx4 v[188:191], v[62:63], off offset:320
	global_load_dwordx4 v[204:207], v[18:19], off offset:384
	global_load_dwordx4 v[208:211], v[62:63], off offset:384
	global_load_dwordx4 v[212:215], v[18:19], off offset:448
	global_load_dwordx4 v[216:219], v[62:63], off offset:448
	global_load_dwordx4 v[220:223], v[18:19], off offset:512
	global_load_dwordx4 v[224:227], v[62:63], off offset:512
	global_load_dwordx4 v[228:231], v[18:19], off offset:576
	global_load_dwordx4 v[232:235], v[62:63], off offset:576
	global_load_dwordx4 v[236:239], v[18:19], off offset:640
	global_load_dwordx4 v[240:243], v[62:63], off offset:640
	global_load_dwordx4 v[244:247], v[18:19], off offset:704
	global_load_dwordx4 v[248:251], v[62:63], off offset:704
	s_waitcnt vmcnt(38)
	v_mfma_f32_16x16x32_bf16 v[4:7], v[68:71], v[72:75], v[4:7]
	global_load_dwordx4 v[68:71], v[18:19], off offset:768
	global_load_dwordx4 v[72:75], v[62:63], off offset:768
	s_waitcnt vmcnt(38)
	v_mfma_f32_16x16x32_bf16 v[0:3], v[76:79], v[80:83], v[0:3]
	global_load_dwordx4 v[76:79], v[18:19], off offset:832
	global_load_dwordx4 v[80:83], v[62:63], off offset:832
	s_waitcnt vmcnt(38)
	v_mfma_f32_16x16x32_bf16 v[4:7], v[84:87], v[88:91], v[4:7]
	global_load_dwordx4 v[84:87], v[18:19], off offset:896
	global_load_dwordx4 v[88:91], v[62:63], off offset:896
	s_waitcnt vmcnt(38)
	v_mfma_f32_16x16x32_bf16 v[0:3], v[92:95], v[96:99], v[0:3]
	global_load_dwordx4 v[92:95], v[18:19], off offset:960
	global_load_dwordx4 v[96:99], v[62:63], off offset:960
	s_waitcnt vmcnt(38)
	v_mfma_f32_16x16x32_bf16 v[4:7], v[100:103], v[104:107], v[4:7]
	global_load_dwordx4 v[100:103], v[18:19], off offset:1024
	global_load_dwordx4 v[104:107], v[62:63], off offset:1024
	s_waitcnt vmcnt(38)
	v_mfma_f32_16x16x32_bf16 v[0:3], v[108:111], v[112:115], v[0:3]
	global_load_dwordx4 v[108:111], v[18:19], off offset:1088
	global_load_dwordx4 v[112:115], v[62:63], off offset:1088
	s_waitcnt vmcnt(38)
	v_mfma_f32_16x16x32_bf16 v[4:7], v[116:119], v[120:123], v[4:7]
	global_load_dwordx4 v[116:119], v[18:19], off offset:1152
	global_load_dwordx4 v[120:123], v[62:63], off offset:1152
	s_waitcnt vmcnt(38)
	v_mfma_f32_16x16x32_bf16 v[0:3], v[124:127], v[128:131], v[0:3]
	global_load_dwordx4 v[124:127], v[18:19], off offset:1216
	global_load_dwordx4 v[128:131], v[62:63], off offset:1216
	s_waitcnt vmcnt(38)
	v_mfma_f32_16x16x32_bf16 v[4:7], v[132:135], v[136:139], v[4:7]
	global_load_dwordx4 v[132:135], v[18:19], off offset:1280
	global_load_dwordx4 v[136:139], v[62:63], off offset:1280
	s_waitcnt vmcnt(38)
	v_mfma_f32_16x16x32_bf16 v[0:3], v[140:143], v[144:147], v[0:3]
	global_load_dwordx4 v[140:143], v[18:19], off offset:1344
	global_load_dwordx4 v[144:147], v[62:63], off offset:1344
	s_waitcnt vmcnt(38)
	v_mfma_f32_16x16x32_bf16 v[4:7], v[148:151], v[164:167], v[4:7]
	global_load_dwordx4 v[148:151], v[18:19], off offset:1408
	global_load_dwordx4 v[164:167], v[62:63], off offset:1408
	s_waitcnt vmcnt(38)
	v_mfma_f32_16x16x32_bf16 v[0:3], v[168:171], v[172:175], v[0:3]
	global_load_dwordx4 v[168:171], v[18:19], off offset:1472
	global_load_dwordx4 v[172:175], v[62:63], off offset:1472
	s_waitcnt vmcnt(38)
	v_mfma_f32_16x16x32_bf16 v[4:7], v[176:179], v[180:183], v[4:7]
	global_load_dwordx4 v[176:179], v[18:19], off offset:1536
	global_load_dwordx4 v[180:183], v[62:63], off offset:1536
	s_waitcnt vmcnt(38)
	v_mfma_f32_16x16x32_bf16 v[0:3], v[184:187], v[188:191], v[0:3]
	global_load_dwordx4 v[184:187], v[18:19], off offset:1600
	global_load_dwordx4 v[188:191], v[62:63], off offset:1600
	s_waitcnt vmcnt(38)
	v_mfma_f32_16x16x32_bf16 v[4:7], v[204:207], v[208:211], v[4:7]
	global_load_dwordx4 v[204:207], v[18:19], off offset:1664
	global_load_dwordx4 v[208:211], v[62:63], off offset:1664
	s_waitcnt vmcnt(38)
	v_mfma_f32_16x16x32_bf16 v[0:3], v[212:215], v[216:219], v[0:3]
	global_load_dwordx4 v[212:215], v[18:19], off offset:1728
	global_load_dwordx4 v[216:219], v[62:63], off offset:1728
	s_waitcnt vmcnt(38)
; __device__ __forceinline__ f32x4 skinny16(const bf16_t* A, int lda, const bf16_t* Bt, int ldb, int K, int lane) {
;     const int r = lane & 15, q = lane >> 4;
;     const bf16x8* ap = (const bf16x8*)(A + (size_t)r * lda + q * 8);
;     const bf16x8* bp = (const bf16x8*)(Bt + (size_t)r * ldb + q * 8);
;     f32x4 acc0 = {0.f, 0.f, 0.f, 0.f}, acc1 = {0.f, 0.f, 0.f, 0.f};
; #pragma unroll 1
;     for (int k = 0; k < K / 32; k += 16) {
;         bf16x8 a[16], b[16];
; #pragma unroll
;         for (int i = 0; i < 16; ++i) { a[i] = ap[(k + i) * 4]; b[i] = bp[(k + i) * 4]; }
; #pragma unroll
;         for (int i = 0; i < 16; i += 2) { acc0 = __builtin_amdgcn_mfma_f32_16x16x32_bf16(a[i], b[i], acc0, 0, 0, 0); acc1 = __builtin_amdgcn_mfma_f32_16x16x32_bf16(a[i + 1], b[i + 1], acc1, 0, 0, 0); }
;     }
;     return acc0 + acc1;
; }
	v_mfma_f32_16x16x32_bf16 v[4:7], v[220:223], v[224:227], v[4:7]
	global_load_dwordx4 v[220:223], v[18:19], off offset:1792
	global_load_dwordx4 v[224:227], v[62:63], off offset:1792
	s_waitcnt vmcnt(38)
	v_mfma_f32_16x16x32_bf16 v[0:3], v[228:231], v[232:235], v[0:3]
	global_load_dwordx4 v[228:231], v[18:19], off offset:1856
	global_load_dwordx4 v[232:235], v[62:63], off offset:1856
	s_waitcnt vmcnt(38)
	v_mfma_f32_16x16x32_bf16 v[4:7], v[236:239], v[240:243], v[4:7]
	global_load_dwordx4 v[236:239], v[18:19], off offset:1920
	global_load_dwordx4 v[240:243], v[62:63], off offset:1920
	s_waitcnt vmcnt(38)
	v_mfma_f32_16x16x32_bf16 v[0:3], v[244:247], v[248:251], v[0:3]
	global_load_dwordx4 v[244:247], v[18:19], off offset:1984
	global_load_dwordx4 v[248:251], v[62:63], off offset:1984
	s_waitcnt vmcnt(38)
	v_mfma_f32_16x16x32_bf16 v[4:7], v[68:71], v[72:75], v[4:7]
	global_load_dwordx4 v[68:71], v[18:19], off offset:2048
	global_load_dwordx4 v[72:75], v[62:63], off offset:2048
	s_waitcnt vmcnt(38)
	v_mfma_f32_16x16x32_bf16 v[0:3], v[76:79], v[80:83], v[0:3]
	global_load_dwordx4 v[76:79], v[18:19], off offset:2112
	global_load_dwordx4 v[80:83], v[62:63], off offset:2112
	s_waitcnt vmcnt(38)
	v_mfma_f32_16x16x32_bf16 v[4:7], v[84:87], v[88:91], v[4:7]
	global_load_dwordx4 v[84:87], v[18:19], off offset:2176
	global_load_dwordx4 v[88:91], v[62:63], off offset:2176
	s_waitcnt vmcnt(38)
	v_mfma_f32_16x16x32_bf16 v[0:3], v[92:95], v[96:99], v[0:3]
	global_load_dwordx4 v[92:95], v[18:19], off offset:2240
	global_load_dwordx4 v[96:99], v[62:63], off offset:2240
	s_waitcnt vmcnt(38)
	v_mfma_f32_16x16x32_bf16 v[4:7], v[100:103], v[104:107], v[4:7]
	global_load_dwordx4 v[100:103], v[18:19], off offset:2304
	global_load_dwordx4 v[104:107], v[62:63], off offset:2304
	s_waitcnt vmcnt(38)
	v_mfma_f32_16x16x32_bf16 v[0:3], v[108:111], v[112:115], v[0:3]
	global_load_dwordx4 v[108:111], v[18:19], off offset:2368
	global_load_dwordx4 v[112:115], v[62:63], off offset:2368
	s_waitcnt vmcnt(38)
	v_mfma_f32_16x16x32_bf16 v[4:7], v[116:119], v[120:123], v[4:7]
	global_load_dwordx4 v[116:119], v[18:19], off offset:2432
	global_load_dwordx4 v[120:123], v[62:63], off offset:2432
	s_waitcnt vmcnt(38)
	v_mfma_f32_16x16x32_bf16 v[0:3], v[124:127], v[128:131], v[0:3]
	global_load_dwordx4 v[124:127], v[18:19], off offset:2496
	global_load_dwordx4 v[128:131], v[62:63], off offset:2496
	s_waitcnt vmcnt(38)
	v_mfma_f32_16x16x32_bf16 v[4:7], v[132:135], v[136:139], v[4:7]
	global_load_dwordx4 v[132:135], v[18:19], off offset:2560
	global_load_dwordx4 v[136:139], v[62:63], off offset:2560
	s_waitcnt vmcnt(38)
	v_mfma_f32_16x16x32_bf16 v[0:3], v[140:143], v[144:147], v[0:3]
	global_load_dwordx4 v[140:143], v[18:19], off offset:2624
	global_load_dwordx4 v[144:147], v[62:63], off offset:2624
	s_waitcnt vmcnt(38)
	v_mfma_f32_16x16x32_bf16 v[4:7], v[148:151], v[164:167], v[4:7]
	global_load_dwordx4 v[148:151], v[18:19], off offset:2688
	global_load_dwordx4 v[164:167], v[62:63], off offset:2688
	s_waitcnt vmcnt(38)
	v_mfma_f32_16x16x32_bf16 v[0:3], v[168:171], v[172:175], v[0:3]
	global_load_dwordx4 v[168:171], v[18:19], off offset:2752
	global_load_dwordx4 v[172:175], v[62:63], off offset:2752
	s_waitcnt vmcnt(38)
	v_mfma_f32_16x16x32_bf16 v[4:7], v[176:179], v[180:183], v[4:7]
	global_load_dwordx4 v[176:179], v[18:19], off offset:2816
	global_load_dwordx4 v[180:183], v[62:63], off offset:2816
	s_waitcnt vmcnt(38)
	v_mfma_f32_16x16x32_bf16 v[0:3], v[184:187], v[188:191], v[0:3]
	global_load_dwordx4 v[184:187], v[18:19], off offset:2880
	global_load_dwordx4 v[188:191], v[62:63], off offset:2880
	s_waitcnt vmcnt(38)
	v_mfma_f32_16x16x32_bf16 v[4:7], v[204:207], v[208:211], v[4:7]
	global_load_dwordx4 v[204:207], v[18:19], off offset:2944
	global_load_dwordx4 v[208:211], v[62:63], off offset:2944
	s_waitcnt vmcnt(38)
	v_mfma_f32_16x16x32_bf16 v[0:3], v[212:215], v[216:219], v[0:3]
	global_load_dwordx4 v[212:215], v[18:19], off offset:3008
	global_load_dwordx4 v[216:219], v[62:63], off offset:3008
	s_waitcnt vmcnt(38)
	v_mfma_f32_16x16x32_bf16 v[4:7], v[220:223], v[224:227], v[4:7]
	global_load_dwordx4 v[220:223], v[18:19], off offset:3072
	global_load_dwordx4 v[224:227], v[62:63], off offset:3072
	s_waitcnt vmcnt(38)
; __device__ __forceinline__ f32x4 skinny16(const bf16_t* A, int lda, const bf16_t* Bt, int ldb, int K, int lane) {
;     const int r = lane & 15, q = lane >> 4;
;     const bf16x8* ap = (const bf16x8*)(A + (size_t)r * lda + q * 8);
;     const bf16x8* bp = (const bf16x8*)(Bt + (size_t)r * ldb + q * 8);
;     f32x4 acc0 = {0.f, 0.f, 0.f, 0.f}, acc1 = {0.f, 0.f, 0.f, 0.f};
; #pragma unroll 1
;     for (int k = 0; k < K / 32; k += 16) {
;         bf16x8 a[16], b[16];
; #pragma unroll
;         for (int i = 0; i < 16; ++i) { a[i] = ap[(k + i) * 4]; b[i] = bp[(k + i) * 4]; }
; #pragma unroll
;         for (int i = 0; i < 16; i += 2) { acc0 = __builtin_amdgcn_mfma_f32_16x16x32_bf16(a[i], b[i], acc0, 0, 0, 0); acc1 = __builtin_amdgcn_mfma_f32_16x16x32_bf16(a[i + 1], b[i + 1], acc1, 0, 0, 0); }
;     }
;     return acc0 + acc1;
; }
; __global__ void __launch_bounds__(512, 2) mega(Args a) {
;     ...
;                 if (task < 8) { const int mt = task;
;                     const f32x4 acc = skinny16(hb + (size_t)(MP + mt * 16) * DM, DM, Wi + (size_t)NZ * DM, DM, DM, lane);
; #pragma unroll
;                     for (int j = 0; j < 4; ++j) zs[(size_t)(mt * 16 + q8 * 4 + j) * DINP + NZ + r] = acc[j];
	v_mfma_f32_16x16x32_bf16 v[0:3], v[228:231], v[232:235], v[0:3]
	global_load_dwordx4 v[228:231], v[18:19], off offset:3136
	global_load_dwordx4 v[232:235], v[62:63], off offset:3136
	s_waitcnt vmcnt(38)
	v_mfma_f32_16x16x32_bf16 v[4:7], v[236:239], v[240:243], v[4:7]
	global_load_dwordx4 v[236:239], v[18:19], off offset:3200
	global_load_dwordx4 v[240:243], v[62:63], off offset:3200
	s_waitcnt vmcnt(38)
	v_mfma_f32_16x16x32_bf16 v[0:3], v[244:247], v[248:251], v[0:3]
	global_load_dwordx4 v[244:247], v[18:19], off offset:3264
	global_load_dwordx4 v[248:251], v[62:63], off offset:3264
	s_waitcnt vmcnt(38)
	v_mfma_f32_16x16x32_bf16 v[4:7], v[68:71], v[72:75], v[4:7]
	global_load_dwordx4 v[68:71], v[18:19], off offset:3328
	global_load_dwordx4 v[72:75], v[62:63], off offset:3328
	s_waitcnt vmcnt(38)
	v_mfma_f32_16x16x32_bf16 v[0:3], v[76:79], v[80:83], v[0:3]
	global_load_dwordx4 v[76:79], v[18:19], off offset:3392
	global_load_dwordx4 v[80:83], v[62:63], off offset:3392
	s_waitcnt vmcnt(38)
	v_mfma_f32_16x16x32_bf16 v[4:7], v[84:87], v[88:91], v[4:7]
	global_load_dwordx4 v[84:87], v[18:19], off offset:3456
	global_load_dwordx4 v[88:91], v[62:63], off offset:3456
	s_waitcnt vmcnt(38)
	v_mfma_f32_16x16x32_bf16 v[0:3], v[92:95], v[96:99], v[0:3]
	global_load_dwordx4 v[92:95], v[18:19], off offset:3520
	global_load_dwordx4 v[96:99], v[62:63], off offset:3520
	s_waitcnt vmcnt(38)
	v_mfma_f32_16x16x32_bf16 v[4:7], v[100:103], v[104:107], v[4:7]
	s_waitcnt vmcnt(36)
	v_mfma_f32_16x16x32_bf16 v[0:3], v[108:111], v[112:115], v[0:3]
	s_waitcnt vmcnt(34)
	v_mfma_f32_16x16x32_bf16 v[4:7], v[116:119], v[120:123], v[4:7]
	s_waitcnt vmcnt(32)
	v_mfma_f32_16x16x32_bf16 v[0:3], v[124:127], v[128:131], v[0:3]
	s_waitcnt vmcnt(30)
	v_mfma_f32_16x16x32_bf16 v[4:7], v[132:135], v[136:139], v[4:7]
	s_waitcnt vmcnt(28)
	v_mfma_f32_16x16x32_bf16 v[0:3], v[140:143], v[144:147], v[0:3]
	s_waitcnt vmcnt(26)
	v_mfma_f32_16x16x32_bf16 v[4:7], v[148:151], v[164:167], v[4:7]
	s_waitcnt vmcnt(24)
	v_mfma_f32_16x16x32_bf16 v[0:3], v[168:171], v[172:175], v[0:3]
	s_waitcnt vmcnt(22)
	v_mfma_f32_16x16x32_bf16 v[4:7], v[176:179], v[180:183], v[4:7]
	s_waitcnt vmcnt(20)
	v_mfma_f32_16x16x32_bf16 v[0:3], v[184:187], v[188:191], v[0:3]
	s_waitcnt vmcnt(18)
	v_mfma_f32_16x16x32_bf16 v[4:7], v[204:207], v[208:211], v[4:7]
	s_waitcnt vmcnt(16)
	v_mfma_f32_16x16x32_bf16 v[0:3], v[212:215], v[216:219], v[0:3]
	s_waitcnt vmcnt(14)
	v_mfma_f32_16x16x32_bf16 v[4:7], v[220:223], v[224:227], v[4:7]
	s_waitcnt vmcnt(12)
	v_mfma_f32_16x16x32_bf16 v[0:3], v[228:231], v[232:235], v[0:3]
	s_waitcnt vmcnt(10)
	v_mfma_f32_16x16x32_bf16 v[4:7], v[236:239], v[240:243], v[4:7]
	s_waitcnt vmcnt(8)
	v_mfma_f32_16x16x32_bf16 v[0:3], v[244:247], v[248:251], v[0:3]
	s_waitcnt vmcnt(6)
	v_mfma_f32_16x16x32_bf16 v[4:7], v[68:71], v[72:75], v[4:7]
	s_waitcnt vmcnt(4)
	v_mfma_f32_16x16x32_bf16 v[0:3], v[76:79], v[80:83], v[0:3]
	s_waitcnt vmcnt(2)
	v_mfma_f32_16x16x32_bf16 v[4:7], v[84:87], v[88:91], v[4:7]
	s_waitcnt vmcnt(0)
	v_mfma_f32_16x16x32_bf16 v[0:3], v[92:95], v[96:99], v[0:3]
	s_nop 1
	s_nop 6
	v_pk_add_f32 v[2:3], v[6:7], v[2:3]
	v_lshl_or_b32 v6, s8, 4, v20
	v_pk_add_f32 v[0:1], v[4:5], v[0:1]
	v_mad_i64_i32 v[4:5], s[6:7], v6, s80, v[158:159]
	v_lshl_add_u64 v[4:5], v[4:5], 0, v[152:153]
	v_add_co_u32_e32 v4, vcc, 0x8000, v4
	s_nop 1
	v_addc_co_u32_e32 v5, vcc, 0, v5, vcc
	global_store_dword v[4:5], v0, off
	v_or_b32_e32 v0, 1, v6
	v_mad_i64_i32 v[4:5], s[6:7], v0, s80, v[158:159]
	v_lshl_add_u64 v[4:5], v[4:5], 0, v[152:153]
	v_add_co_u32_e32 v4, vcc, 0x8000, v4
	v_or_b32_e32 v0, 2, v6
	s_nop 0
	v_addc_co_u32_e32 v5, vcc, 0, v5, vcc
	global_store_dword v[4:5], v1, off
	v_mad_i64_i32 v[0:1], s[6:7], v0, s80, v[158:159]
	v_lshl_add_u64 v[0:1], v[0:1], 0, v[152:153]
	v_add_co_u32_e32 v0, vcc, 0x8000, v0
	s_nop 1
	v_addc_co_u32_e32 v1, vcc, 0, v1, vcc
	global_store_dword v[0:1], v2, off
	v_or_b32_e32 v0, 3, v6
	v_mad_i64_i32 v[0:1], s[6:7], v0, s80, v[158:159]
	v_lshl_add_u64 v[0:1], v[0:1], 0, v[152:153]
	v_add_co_u32_e32 v0, vcc, 0x8000, v0
	s_nop 1
	v_addc_co_u32_e32 v1, vcc, 0, v1, vcc
	global_store_dword v[0:1], v3, off
	s_branch .LBB0_360

; __device__ __forceinline__ f32x4 skinny16(const bf16_t* A, int lda, const bf16_t* Bt, int ldb, int K, int lane) {
;     const int r = lane & 15, q = lane >> 4;
;     const bf16x8* ap = (const bf16x8*)(A + (size_t)r * lda + q * 8);
;     const bf16x8* bp = (const bf16x8*)(Bt + (size_t)r * ldb + q * 8);
;     f32x4 acc0 = {0.f, 0.f, 0.f, 0.f}, acc1 = {0.f, 0.f, 0.f, 0.f};
; #pragma unroll 1
;     for (int k = 0; k < K / 32; k += 16) {
;         bf16x8 a[16], b[16];
; #pragma unroll
;         for (int i = 0; i < 16; ++i) { a[i] = ap[(k + i) * 4]; b[i] = bp[(k + i) * 4]; }
; #pragma unroll
;         for (int i = 0; i < 16; i += 2) { acc0 = __builtin_amdgcn_mfma_f32_16x16x32_bf16(a[i], b[i], acc0, 0, 0, 0); acc1 = __builtin_amdgcn_mfma_f32_16x16x32_bf16(a[i + 1], b[i + 1], acc1, 0, 0, 0); }
;     }
;     return acc0 + acc1;
; }
; __global__ void __launch_bounds__(512, 2) mega(Args a) {
;     ...
;                 const int task = wave * G + bx, mt = task & 7, nt = task >> 3;
;                 const f32x4 acc = skinny16(ycat + (size_t)(MP + mt * 16) * DM, DM, Wo + (size_t)nt * 16 * DM, DM, DM, lane);
.LBB0_584:
	global_load_dwordx4 v[68:71], v[12:13], off offset:-512
	global_load_dwordx4 v[72:75], v[10:11], off offset:-960
	global_load_dwordx4 v[76:79], v[12:13], off offset:-448
	global_load_dwordx4 v[80:83], v[10:11], off offset:-896
	global_load_dwordx4 v[84:87], v[12:13], off offset:-384
	global_load_dwordx4 v[88:91], v[10:11], off offset:-832
	global_load_dwordx4 v[92:95], v[12:13], off offset:-320
	global_load_dwordx4 v[96:99], v[10:11], off offset:-768
	global_load_dwordx4 v[100:103], v[12:13], off offset:-256
	global_load_dwordx4 v[104:107], v[10:11], off offset:-704
	global_load_dwordx4 v[108:111], v[12:13], off offset:-192
	global_load_dwordx4 v[112:115], v[10:11], off offset:-640
	global_load_dwordx4 v[116:119], v[12:13], off offset:-128
	global_load_dwordx4 v[120:123], v[10:11], off offset:-576
	global_load_dwordx4 v[124:127], v[12:13], off offset:-64
	global_load_dwordx4 v[128:131], v[10:11], off offset:-512
	global_load_dwordx4 v[132:135], v[12:13], off offset:0
	global_load_dwordx4 v[136:139], v[10:11], off offset:-448
	global_load_dwordx4 v[140:143], v[12:13], off offset:64
	global_load_dwordx4 v[144:147], v[10:11], off offset:-384
	global_load_dwordx4 v[148:151], v[12:13], off offset:128
	global_load_dwordx4 v[164:167], v[10:11], off offset:-320
	global_load_dwordx4 v[168:171], v[12:13], off offset:192
	global_load_dwordx4 v[172:175], v[10:11], off offset:-256
	global_load_dwordx4 v[176:179], v[12:13], off offset:256
	global_load_dwordx4 v[180:183], v[10:11], off offset:-192
	global_load_dwordx4 v[184:187], v[12:13], off offset:320
	global_load_dwordx4 v[188:191], v[10:11], off offset:-128
	global_load_dwordx4 v[204:207], v[12:13], off offset:384
	global_load_dwordx4 v[208:211], v[10:11], off offset:-64
	global_load_dwordx4 v[212:215], v[12:13], off offset:448
	global_load_dwordx4 v[216:219], v[10:11], off offset:0
	global_load_dwordx4 v[220:223], v[12:13], off offset:512
	global_load_dwordx4 v[224:227], v[10:11], off offset:64
	global_load_dwordx4 v[228:231], v[12:13], off offset:576
	global_load_dwordx4 v[232:235], v[10:11], off offset:128
	global_load_dwordx4 v[236:239], v[12:13], off offset:640
	global_load_dwordx4 v[240:243], v[10:11], off offset:192
	global_load_dwordx4 v[244:247], v[12:13], off offset:704
	global_load_dwordx4 v[248:251], v[10:11], off offset:256
	s_waitcnt vmcnt(38)
	v_mfma_f32_16x16x32_bf16 v[4:7], v[68:71], v[72:75], v[4:7]
	global_load_dwordx4 v[68:71], v[12:13], off offset:768
	global_load_dwordx4 v[72:75], v[10:11], off offset:320
	s_waitcnt vmcnt(38)
	v_mfma_f32_16x16x32_bf16 v[0:3], v[76:79], v[80:83], v[0:3]
	global_load_dwordx4 v[76:79], v[12:13], off offset:832
	global_load_dwordx4 v[80:83], v[10:11], off offset:384
	s_waitcnt vmcnt(38)
	v_mfma_f32_16x16x32_bf16 v[4:7], v[84:87], v[88:91], v[4:7]
	global_load_dwordx4 v[84:87], v[12:13], off offset:896
	global_load_dwordx4 v[88:91], v[10:11], off offset:448
	s_waitcnt vmcnt(38)
	v_mfma_f32_16x16x32_bf16 v[0:3], v[92:95], v[96:99], v[0:3]
	global_load_dwordx4 v[92:95], v[12:13], off offset:960
	global_load_dwordx4 v[96:99], v[10:11], off offset:512
	s_waitcnt vmcnt(38)
	v_mfma_f32_16x16x32_bf16 v[4:7], v[100:103], v[104:107], v[4:7]
	global_load_dwordx4 v[100:103], v[12:13], off offset:1024
	global_load_dwordx4 v[104:107], v[10:11], off offset:576
	s_waitcnt vmcnt(38)
	v_mfma_f32_16x16x32_bf16 v[0:3], v[108:111], v[112:115], v[0:3]
	global_load_dwordx4 v[108:111], v[12:13], off offset:1088
	global_load_dwordx4 v[112:115], v[10:11], off offset:640
	s_waitcnt vmcnt(38)
	v_mfma_f32_16x16x32_bf16 v[4:7], v[116:119], v[120:123], v[4:7]
	global_load_dwordx4 v[116:119], v[12:13], off offset:1152
	global_load_dwordx4 v[120:123], v[10:11], off offset:704
	s_waitcnt vmcnt(38)
	v_mfma_f32_16x16x32_bf16 v[0:3], v[124:127], v[128:131], v[0:3]
	global_load_dwordx4 v[124:127], v[12:13], off offset:1216
	global_load_dwordx4 v[128:131], v[10:11], off offset:768
	s_waitcnt vmcnt(38)
	v_mfma_f32_16x16x32_bf16 v[4:7], v[132:135], v[136:139], v[4:7]
	global_load_dwordx4 v[132:135], v[12:13], off offset:1280
	global_load_dwordx4 v[136:139], v[10:11], off offset:832
	s_waitcnt vmcnt(38)
	v_mfma_f32_16x16x32_bf16 v[0:3], v[140:143], v[144:147], v[0:3]
	global_load_dwordx4 v[140:143], v[12:13], off offset:1344
	global_load_dwordx4 v[144:147], v[10:11], off offset:896
	s_waitcnt vmcnt(38)
	v_mfma_f32_16x16x32_bf16 v[4:7], v[148:151], v[164:167], v[4:7]
	global_load_dwordx4 v[148:151], v[12:13], off offset:1408
	global_load_dwordx4 v[164:167], v[10:11], off offset:960
	s_waitcnt vmcnt(38)
	v_mfma_f32_16x16x32_bf16 v[0:3], v[168:171], v[172:175], v[0:3]
	global_load_dwordx4 v[168:171], v[12:13], off offset:1472
	global_load_dwordx4 v[172:175], v[10:11], off offset:1024
	s_waitcnt vmcnt(38)
	v_mfma_f32_16x16x32_bf16 v[4:7], v[176:179], v[180:183], v[4:7]
	global_load_dwordx4 v[176:179], v[12:13], off offset:1536
	global_load_dwordx4 v[180:183], v[10:11], off offset:1088
	s_waitcnt vmcnt(38)
	v_mfma_f32_16x16x32_bf16 v[0:3], v[184:187], v[188:191], v[0:3]
	global_load_dwordx4 v[184:187], v[12:13], off offset:1600
	global_load_dwordx4 v[188:191], v[10:11], off offset:1152
	s_waitcnt vmcnt(38)
	v_mfma_f32_16x16x32_bf16 v[4:7], v[204:207], v[208:211], v[4:7]
	global_load_dwordx4 v[204:207], v[12:13], off offset:1664
	global_load_dwordx4 v[208:211], v[10:11], off offset:1216
	s_waitcnt vmcnt(38)
	v_mfma_f32_16x16x32_bf16 v[0:3], v[212:215], v[216:219], v[0:3]
	global_load_dwordx4 v[212:215], v[12:13], off offset:1728
	global_load_dwordx4 v[216:219], v[10:11], off offset:1280
	s_waitcnt vmcnt(38)
; __device__ __forceinline__ f32x4 skinny16(const bf16_t* A, int lda, const bf16_t* Bt, int ldb, int K, int lane) {
;     const int r = lane & 15, q = lane >> 4;
;     const bf16x8* ap = (const bf16x8*)(A + (size_t)r * lda + q * 8);
;     const bf16x8* bp = (const bf16x8*)(Bt + (size_t)r * ldb + q * 8);
;     f32x4 acc0 = {0.f, 0.f, 0.f, 0.f}, acc1 = {0.f, 0.f, 0.f, 0.f};
; #pragma unroll 1
;     for (int k = 0; k < K / 32; k += 16) {
;         bf16x8 a[16], b[16];
; #pragma unroll
;         for (int i = 0; i < 16; ++i) { a[i] = ap[(k + i) * 4]; b[i] = bp[(k + i) * 4]; }
; #pragma unroll
;         for (int i = 0; i < 16; i += 2) { acc0 = __builtin_amdgcn_mfma_f32_16x16x32_bf16(a[i], b[i], acc0, 0, 0, 0); acc1 = __builtin_amdgcn_mfma_f32_16x16x32_bf16(a[i + 1], b[i + 1], acc1, 0, 0, 0); }
;     }
;     return acc0 + acc1;
; }
	v_mfma_f32_16x16x32_bf16 v[4:7], v[220:223], v[224:227], v[4:7]
	global_load_dwordx4 v[220:223], v[12:13], off offset:1792
	global_load_dwordx4 v[224:227], v[10:11], off offset:1344
	s_waitcnt vmcnt(38)
	v_mfma_f32_16x16x32_bf16 v[0:3], v[228:231], v[232:235], v[0:3]
	global_load_dwordx4 v[228:231], v[12:13], off offset:1856
	global_load_dwordx4 v[232:235], v[10:11], off offset:1408
	s_waitcnt vmcnt(38)
	v_mfma_f32_16x16x32_bf16 v[4:7], v[236:239], v[240:243], v[4:7]
	global_load_dwordx4 v[236:239], v[12:13], off offset:1920
	global_load_dwordx4 v[240:243], v[10:11], off offset:1472
	s_waitcnt vmcnt(38)
	v_mfma_f32_16x16x32_bf16 v[0:3], v[244:247], v[248:251], v[0:3]
	global_load_dwordx4 v[244:247], v[12:13], off offset:1984
	global_load_dwordx4 v[248:251], v[10:11], off offset:1536
	s_waitcnt vmcnt(38)
	v_mfma_f32_16x16x32_bf16 v[4:7], v[68:71], v[72:75], v[4:7]
	global_load_dwordx4 v[68:71], v[12:13], off offset:2048
	global_load_dwordx4 v[72:75], v[10:11], off offset:1600
	s_waitcnt vmcnt(38)
	v_mfma_f32_16x16x32_bf16 v[0:3], v[76:79], v[80:83], v[0:3]
	global_load_dwordx4 v[76:79], v[12:13], off offset:2112
	global_load_dwordx4 v[80:83], v[10:11], off offset:1664
	s_waitcnt vmcnt(38)
	v_mfma_f32_16x16x32_bf16 v[4:7], v[84:87], v[88:91], v[4:7]
	global_load_dwordx4 v[84:87], v[12:13], off offset:2176
	global_load_dwordx4 v[88:91], v[10:11], off offset:1728
	s_waitcnt vmcnt(38)
	v_mfma_f32_16x16x32_bf16 v[0:3], v[92:95], v[96:99], v[0:3]
	global_load_dwordx4 v[92:95], v[12:13], off offset:2240
	global_load_dwordx4 v[96:99], v[10:11], off offset:1792
	s_waitcnt vmcnt(38)
	v_mfma_f32_16x16x32_bf16 v[4:7], v[100:103], v[104:107], v[4:7]
	global_load_dwordx4 v[100:103], v[12:13], off offset:2304
	global_load_dwordx4 v[104:107], v[10:11], off offset:1856
	s_waitcnt vmcnt(38)
	v_mfma_f32_16x16x32_bf16 v[0:3], v[108:111], v[112:115], v[0:3]
	global_load_dwordx4 v[108:111], v[12:13], off offset:2368
	global_load_dwordx4 v[112:115], v[10:11], off offset:1920
	s_waitcnt vmcnt(38)
	v_mfma_f32_16x16x32_bf16 v[4:7], v[116:119], v[120:123], v[4:7]
	global_load_dwordx4 v[116:119], v[12:13], off offset:2432
	global_load_dwordx4 v[120:123], v[10:11], off offset:1984
	s_waitcnt vmcnt(38)
	v_mfma_f32_16x16x32_bf16 v[0:3], v[124:127], v[128:131], v[0:3]
	global_load_dwordx4 v[124:127], v[12:13], off offset:2496
	global_load_dwordx4 v[128:131], v[10:11], off offset:2048
	s_waitcnt vmcnt(38)
	v_mfma_f32_16x16x32_bf16 v[4:7], v[132:135], v[136:139], v[4:7]
	global_load_dwordx4 v[132:135], v[12:13], off offset:2560
	global_load_dwordx4 v[136:139], v[10:11], off offset:2112
	s_waitcnt vmcnt(38)
	v_mfma_f32_16x16x32_bf16 v[0:3], v[140:143], v[144:147], v[0:3]
	global_load_dwordx4 v[140:143], v[12:13], off offset:2624
	global_load_dwordx4 v[144:147], v[10:11], off offset:2176
	s_waitcnt vmcnt(38)
	v_mfma_f32_16x16x32_bf16 v[4:7], v[148:151], v[164:167], v[4:7]
	global_load_dwordx4 v[148:151], v[12:13], off offset:2688
	global_load_dwordx4 v[164:167], v[10:11], off offset:2240
	s_waitcnt vmcnt(38)
	v_mfma_f32_16x16x32_bf16 v[0:3], v[168:171], v[172:175], v[0:3]
	global_load_dwordx4 v[168:171], v[12:13], off offset:2752
	global_load_dwordx4 v[172:175], v[10:11], off offset:2304
	s_waitcnt vmcnt(38)
	v_mfma_f32_16x16x32_bf16 v[4:7], v[176:179], v[180:183], v[4:7]
	global_load_dwordx4 v[176:179], v[12:13], off offset:2816
	global_load_dwordx4 v[180:183], v[10:11], off offset:2368
	s_waitcnt vmcnt(38)
	v_mfma_f32_16x16x32_bf16 v[0:3], v[184:187], v[188:191], v[0:3]
	global_load_dwordx4 v[184:187], v[12:13], off offset:2880
	global_load_dwordx4 v[188:191], v[10:11], off offset:2432
	s_waitcnt vmcnt(38)
	v_mfma_f32_16x16x32_bf16 v[4:7], v[204:207], v[208:211], v[4:7]
	global_load_dwordx4 v[204:207], v[12:13], off offset:2944
	global_load_dwordx4 v[208:211], v[10:11], off offset:2496
	s_waitcnt vmcnt(38)
	v_mfma_f32_16x16x32_bf16 v[0:3], v[212:215], v[216:219], v[0:3]
	global_load_dwordx4 v[212:215], v[12:13], off offset:3008
	global_load_dwordx4 v[216:219], v[10:11], off offset:2560
	s_waitcnt vmcnt(38)
	v_mfma_f32_16x16x32_bf16 v[4:7], v[220:223], v[224:227], v[4:7]
	global_load_dwordx4 v[220:223], v[12:13], off offset:3072
	global_load_dwordx4 v[224:227], v[10:11], off offset:2624
	s_waitcnt vmcnt(38)
	v_mfma_f32_16x16x32_bf16 v[0:3], v[228:231], v[232:235], v[0:3]
	global_load_dwordx4 v[228:231], v[12:13], off offset:3136
	global_load_dwordx4 v[232:235], v[10:11], off offset:2688
	s_waitcnt vmcnt(38)
	v_mfma_f32_16x16x32_bf16 v[4:7], v[236:239], v[240:243], v[4:7]
	global_load_dwordx4 v[236:239], v[12:13], off offset:3200
	global_load_dwordx4 v[240:243], v[10:11], off offset:2752
	s_waitcnt vmcnt(38)
	v_mfma_f32_16x16x32_bf16 v[0:3], v[244:247], v[248:251], v[0:3]
	global_load_dwordx4 v[244:247], v[12:13], off offset:3264
	global_load_dwordx4 v[248:251], v[10:11], off offset:2816
	s_waitcnt vmcnt(38)
	v_mfma_f32_16x16x32_bf16 v[4:7], v[68:71], v[72:75], v[4:7]
	global_load_dwordx4 v[68:71], v[12:13], off offset:3328
	global_load_dwordx4 v[72:75], v[10:11], off offset:2880
	s_waitcnt vmcnt(38)
; __device__ __forceinline__ f32x4 skinny16(const bf16_t* A, int lda, const bf16_t* Bt, int ldb, int K, int lane) {
;     ...
;     for (int k = 0; k < K / 32; k += 16) {
;         bf16x8 a[16], b[16];
; #pragma unroll
;         for (int i = 0; i < 16; ++i) { a[i] = ap[(k + i) * 4]; b[i] = bp[(k + i) * 4]; }
; #pragma unroll
;         for (int i = 0; i < 16; i += 2) { acc0 = __builtin_amdgcn_mfma_f32_16x16x32_bf16(a[i], b[i], acc0, 0, 0, 0); acc1 = __builtin_amdgcn_mfma_f32_16x16x32_bf16(a[i + 1], b[i + 1], acc1, 0, 0, 0); }
;     }
;     return acc0 + acc1;
; }
; __global__ void __launch_bounds__(512, 2) mega(Args a) {
;     ...
;                 const int task = wave * G + bx, mt = task & 7, nt = task >> 3;
;                 const f32x4 acc = skinny16(ycat + (size_t)(MP + mt * 16) * DM, DM, Wo + (size_t)nt * 16 * DM, DM, DM, lane);
; #pragma unroll
;                 for (int j = 0; j < 4; ++j) { const int row = mt * 16 + q8 * 4 + j, col = nt * 16 + r;
;                     xcur[(size_t)(MP + row) * DM + col] = xb[(size_t)row * DM + col] + modg[(size_t)(NB + row) * MODLD + col] * acc[j]; }
	v_mfma_f32_16x16x32_bf16 v[0:3], v[76:79], v[80:83], v[0:3]
	global_load_dwordx4 v[76:79], v[12:13], off offset:3392
	global_load_dwordx4 v[80:83], v[10:11], off offset:2944
	s_waitcnt vmcnt(38)
	v_mfma_f32_16x16x32_bf16 v[4:7], v[84:87], v[88:91], v[4:7]
	global_load_dwordx4 v[84:87], v[12:13], off offset:3456
	global_load_dwordx4 v[88:91], v[10:11], off offset:3008
	s_waitcnt vmcnt(38)
	v_mfma_f32_16x16x32_bf16 v[0:3], v[92:95], v[96:99], v[0:3]
	global_load_dwordx4 v[92:95], v[12:13], off offset:3520
	global_load_dwordx4 v[96:99], v[10:11], off offset:3072
	s_waitcnt vmcnt(38)
	v_mfma_f32_16x16x32_bf16 v[4:7], v[100:103], v[104:107], v[4:7]
	s_waitcnt vmcnt(36)
	v_mfma_f32_16x16x32_bf16 v[0:3], v[108:111], v[112:115], v[0:3]
	s_waitcnt vmcnt(34)
	v_mfma_f32_16x16x32_bf16 v[4:7], v[116:119], v[120:123], v[4:7]
	s_waitcnt vmcnt(32)
	v_mfma_f32_16x16x32_bf16 v[0:3], v[124:127], v[128:131], v[0:3]
	s_waitcnt vmcnt(30)
	v_mfma_f32_16x16x32_bf16 v[4:7], v[132:135], v[136:139], v[4:7]
	s_waitcnt vmcnt(28)
	v_mfma_f32_16x16x32_bf16 v[0:3], v[140:143], v[144:147], v[0:3]
	s_waitcnt vmcnt(26)
	v_mfma_f32_16x16x32_bf16 v[4:7], v[148:151], v[164:167], v[4:7]
	s_waitcnt vmcnt(24)
	v_mfma_f32_16x16x32_bf16 v[0:3], v[168:171], v[172:175], v[0:3]
	s_waitcnt vmcnt(22)
	v_mfma_f32_16x16x32_bf16 v[4:7], v[176:179], v[180:183], v[4:7]
	s_waitcnt vmcnt(20)
	v_mfma_f32_16x16x32_bf16 v[0:3], v[184:187], v[188:191], v[0:3]
	s_waitcnt vmcnt(18)
	v_mfma_f32_16x16x32_bf16 v[4:7], v[204:207], v[208:211], v[4:7]
	s_waitcnt vmcnt(16)
	v_mfma_f32_16x16x32_bf16 v[0:3], v[212:215], v[216:219], v[0:3]
	s_waitcnt vmcnt(14)
	v_mfma_f32_16x16x32_bf16 v[4:7], v[220:223], v[224:227], v[4:7]
	s_waitcnt vmcnt(12)
	v_mfma_f32_16x16x32_bf16 v[0:3], v[228:231], v[232:235], v[0:3]
	s_waitcnt vmcnt(10)
	v_mfma_f32_16x16x32_bf16 v[4:7], v[236:239], v[240:243], v[4:7]
	s_waitcnt vmcnt(8)
	v_mfma_f32_16x16x32_bf16 v[0:3], v[244:247], v[248:251], v[0:3]
	s_waitcnt vmcnt(6)
	v_mfma_f32_16x16x32_bf16 v[4:7], v[68:71], v[72:75], v[4:7]
	s_waitcnt vmcnt(4)
	v_mfma_f32_16x16x32_bf16 v[0:3], v[76:79], v[80:83], v[0:3]
	s_waitcnt vmcnt(2)
	v_mfma_f32_16x16x32_bf16 v[4:7], v[84:87], v[88:91], v[4:7]
	s_waitcnt vmcnt(0)
	v_mfma_f32_16x16x32_bf16 v[0:3], v[92:95], v[96:99], v[0:3]
	s_nop 1
	s_lshl_b32 s7, s8, 4
	s_and_b32 s7, s7, 0x70
	v_and_b32_e32 v12, 15, v14
	s_nop 3
	v_pk_add_f32 v[4:5], v[4:5], v[0:1]
	v_lshrrev_b32_e32 v0, 2, v14
	v_and_or_b32 v13, v0, 12, s7
	v_lshl_or_b32 v0, s6, 4, v12
	v_ashrrev_i32_e32 v1, 31, v0
	v_lshlrev_b64 v[0:1], 2, v[0:1]
	v_pk_add_f32 v[2:3], v[6:7], v[2:3]
	v_lshl_add_u64 v[6:7], v[8:9], 0, v[0:1]
	v_lshlrev_b32_e32 v152, 13, v13
	v_readlane_b32 s10, v254, 8
	v_lshl_add_u64 v[8:9], v[6:7], 0, v[152:153]
	v_readlane_b32 s11, v254, 9
	global_load_dword v12, v[8:9], off
	v_mul_u32_u24_e32 v8, 0x6000, v13
	v_lshl_add_u64 v[10:11], s[10:11], 2, v[28:29]
	v_lshlrev_b32_e32 v8, 2, v8
	v_mov_b32_e32 v9, v153
	v_lshl_add_u64 v[8:9], v[10:11], 0, v[8:9]
	v_lshl_add_u64 v[8:9], v[8:9], 0, v[0:1]
	s_mov_b32 s6, 0x10364000
	v_add_co_u32_e32 v10, vcc, s6, v8
	s_mov_b32 s7, 0x20200000
	s_nop 0
	v_addc_co_u32_e32 v11, vcc, 0, v9, vcc
	global_load_dword v10, v[10:11], off
	s_mov_b32 s6, 0x1037c000
	s_waitcnt vmcnt(0)
	v_fmac_f32_e32 v12, v4, v10
	v_lshl_add_u64 v[10:11], v[28:29], 0, v[152:153]
	v_lshl_add_u64 v[10:11], v[10:11], 0, v[0:1]
	v_add_co_u32_e32 v10, vcc, s7, v10
	s_nop 1
	v_addc_co_u32_e32 v11, vcc, 0, v11, vcc
	global_store_dword v[10:11], v12, off
	v_or_b32_e32 v10, 0x2000, v152
	v_mov_b32_e32 v11, v153
	v_lshl_add_u64 v[12:13], v[6:7], 0, v[10:11]
	global_load_dword v14, v[12:13], off
	v_add_co_u32_e32 v12, vcc, s6, v8
	s_mov_b32 s6, 0x10394000
	s_nop 0
	v_addc_co_u32_e32 v13, vcc, 0, v9, vcc
	global_load_dword v4, v[12:13], off
	s_waitcnt vmcnt(0)
	v_fmac_f32_e32 v14, v5, v4
	v_lshl_add_u64 v[4:5], v[28:29], 0, v[10:11]
	v_lshl_add_u64 v[4:5], v[4:5], 0, v[0:1]
	v_add_co_u32_e32 v4, vcc, s7, v4
	s_nop 1
	v_addc_co_u32_e32 v5, vcc, 0, v5, vcc
	global_store_dword v[4:5], v14, off
	v_or_b32_e32 v4, 0x4000, v152
	v_mov_b32_e32 v5, v153
	v_lshl_add_u64 v[10:11], v[6:7], 0, v[4:5]
	global_load_dword v12, v[10:11], off
	v_add_co_u32_e32 v10, vcc, s6, v8
	v_lshl_add_u64 v[4:5], v[28:29], 0, v[4:5]
	s_nop 0
	v_addc_co_u32_e32 v11, vcc, 0, v9, vcc
	global_load_dword v10, v[10:11], off
	v_lshl_add_u64 v[4:5], v[4:5], 0, v[0:1]
	v_add_co_u32_e32 v4, vcc, s7, v4
	v_or_b32_e32 v152, 0x6000, v152
	s_nop 0
	v_addc_co_u32_e32 v5, vcc, 0, v5, vcc
	s_mov_b64 s[6:7], 0
	s_waitcnt vmcnt(0)
	v_fmac_f32_e32 v12, v2, v10
	global_store_dword v[4:5], v12, off
	v_lshl_add_u64 v[4:5], v[6:7], 0, v[152:153]
	global_load_dword v6, v[4:5], off
	v_add_co_u32_e32 v4, vcc, 0x103ac000, v8
	s_nop 1
	v_addc_co_u32_e32 v5, vcc, 0, v9, vcc
	global_load_dword v2, v[4:5], off
	s_waitcnt vmcnt(0)
	v_fmac_f32_e32 v6, v3, v2
	v_lshl_add_u64 v[2:3], v[28:29], 0, v[152:153]
	v_lshl_add_u64 v[0:1], v[2:3], 0, v[0:1]
	v_add_co_u32_e32 v0, vcc, 0x20200000, v0
	s_nop 1
	v_addc_co_u32_e32 v1, vcc, 0, v1, vcc
	global_store_dword v[0:1], v6, off
